# split-K tail items P4a/P4b/P5/P8: epilogue gate/residual loads issued at item start, 8 LDS partial reads in flight
# baseline (speedup 1.0000x reference)
; #define LAS __attribute__((address_space(3)))
; #define MFMA16(a, b, c) __builtin_amdgcn_mfma_f32_16x16x32_bf16((a), (b), (c), 0, 0, 0)
;     __device__ __forceinline__ void quad(int row, int c, f32x4 v) const {
;         const u32x2 gw = *(const u32x2*)(Z + (size_t)row * NZ + ZC_MA + c);
; template <int MT, int NT, class Epi>
; __device__ __forceinline__ void tail_splitk(LAS unsigned char* lds, const bf16_t* A, const bf16_t* Bt, int K, int row_base, int n_rt, int col_base, int n_ct, int it0, const Epi& E) {
;     ...
;     for (int it = (bid - it0 + G) % G; it < n_rt * n_ct; it += G) {
;         const int rt = it % n_rt, ct = it / n_rt, r0 = row_base + rt * 16 * MT, c0 = col_base + ct * 16 * NT;
;         f32x4 acc[MT][NT];
; #pragma unroll
;         for (int mt = 0; mt < MT; ++mt)
; #pragma unroll
;             for (int nt = 0; nt < NT; ++nt) acc[mt][nt] = (f32x4){0.f, 0.f, 0.f, 0.f};
;         const bf16_t* ap = A + (size_t)(r0 + fr) * K + fq * 8 + w * nks * 32; const bf16_t* bp = Bt + (size_t)(c0 + fr) * K + fq * 8 + w * nks * 32;
; #pragma unroll 4
;         for (int ks = 0; ks < nks; ++ks) {
;             bf16x8 af[MT], bfv[NT];
; #pragma unroll
;             for (int mt = 0; mt < MT; ++mt) af[mt] = *(const bf16x8*)(ap + (size_t)mt * 16 * K + ks * 32);
; #pragma unroll
;             for (int nt = 0; nt < NT; ++nt) bfv[nt] = *(const bf16x8*)(bp + (size_t)nt * 16 * K + ks * 32);
; #pragma unroll
;             for (int mt = 0; mt < MT; ++mt)
; #pragma unroll
;                 for (int nt = 0; nt < NT; ++nt) acc[mt][nt] = MFMA16(bfv[nt], af[mt], acc[mt][nt]);
;         }
;         LAS float* pw = (LAS float*)(lds + w * WB);
; #pragma unroll
;         for (int mt = 0; mt < MT; ++mt)
; #pragma unroll
;             for (int nt = 0; nt < NT; ++nt) *(LAS f32x4*)(pw + (16 * mt + fr) * RS + 16 * nt + 4 * fq) = acc[mt][nt];
;         __syncthreads();
.LBB0_718:
	s_ashr_i32 s0, s14, 31
	s_lshr_b32 s0, s0, 29
	s_add_i32 s0, s14, s0
	s_and_b32 s1, s0, 0x7fffff8
	s_lshl_b32 s12, s0, 3
	s_sub_i32 s1, s14, s1
	s_andn2_b32 s12, s12, 63
	s_lshl_b32 s15, s1, 5
	v_or_b32_e32 v6, s12, v9
	s_addk_i32 s15, 0x4000
	v_ashrrev_i32_e32 v7, 31, v6
	v_lshlrev_b64 v[6:7], 11, v[6:7]
	v_or_b32_e32 v0, s15, v9
	v_lshl_add_u64 v[66:67], v[4:5], 0, v[6:7]
	v_lshlrev_b64 v[6:7], 11, v[0:1]
	v_lshl_add_u64 v[68:69], v[2:3], 0, v[6:7]
	v_add_co_u32_e64 v6, s[0:1], s64, v68
	v_ashrrev_i32_e32 v48, 4, v8
	v_lshlrev_b32_e32 v49, 6, v48
	v_add_u32_e32 v50, s12, v10
	v_sub_u32_e32 v50, v50, v49
	v_add_u32_e32 v52, s15, v48
	v_ashrrev_i32_e32 v51, 31, v50
	v_ashrrev_i32_e32 v53, 31, v52
	v_mov_b64_e32 v[54:55], s[34:35]
	v_mad_i64_i32 v[54:55], s[86:87], v52, s67, v[54:55]
	v_lshlrev_b64 v[60:61], 1, v[50:51]
	v_lshl_add_u64 v[54:55], v[54:55], 0, v[60:61]
	v_add_co_u32_e64 v54, s[86:87], s7, v54
	s_nop 1
	v_addc_co_u32_e64 v55, s[86:87], 0, v55, s[86:87]
	global_load_dwordx2 v[46:47], v[54:55], off offset:2048
	global_load_dwordx4 v[76:79], v[66:67], off
	global_load_dwordx4 v[80:83], v[66:67], off offset:64
	v_addc_co_u32_e64 v7, s[0:1], 0, v69, s[0:1]
	v_add_co_u32_e64 v70, s[0:1], s64, v66
	global_load_dwordx4 v[84:87], v[68:69], off
	s_nop 0
	v_addc_co_u32_e64 v71, s[0:1], 0, v67, s[0:1]
	v_add_co_u32_e64 v72, s[0:1], s33, v66
	global_load_dwordx4 v[88:91], v[70:71], off
	s_nop 0
	v_addc_co_u32_e64 v73, s[0:1], 0, v67, s[0:1]
	v_add_co_u32_e64 v74, s[0:1], s6, v66
	global_load_dwordx4 v[92:95], v[72:73], off
	s_nop 0
	v_addc_co_u32_e64 v75, s[0:1], 0, v67, s[0:1]
	global_load_dwordx4 v[96:99], v[74:75], off
	global_load_dwordx4 v[100:103], v[6:7], off
	global_load_dwordx4 v[104:107], v[6:7], off offset:64
	s_nop 0
	s_nop 0
	global_load_dwordx4 v[108:111], v[72:73], off offset:64
	global_load_dwordx4 v[112:115], v[74:75], off offset:64
	s_nop 0
	s_nop 0
	s_nop 0
	global_load_dwordx4 v[116:119], v[68:69], off offset:64
	s_nop 0
	s_nop 0
	s_nop 0
	global_load_dwordx4 v[120:123], v[70:71], off offset:64
	s_nop 0
	s_nop 0
	global_load_dwordx4 v[124:127], v[72:73], off offset:128
	s_nop 0
	s_nop 0
	s_nop 0
	global_load_dwordx4 v[148:151], v[66:67], off offset:128
	s_nop 0
	global_load_dwordx4 v[152:155], v[68:69], off offset:128
	s_nop 0
	global_load_dwordx4 v[164:167], v[6:7], off offset:128
	global_load_dwordx4 v[168:171], v[74:75], off offset:128
	s_nop 0
	s_nop 0
	s_nop 0
	global_load_dwordx4 v[172:175], v[70:71], off offset:128
	s_nop 0
	s_nop 0
	s_nop 0
	global_load_dwordx4 v[176:179], v[72:73], off offset:192
	s_nop 0
	global_load_dwordx4 v[180:183], v[74:75], off offset:192
	s_nop 0
	s_nop 0
	global_load_dwordx4 v[184:187], v[68:69], off offset:192
	s_nop 0
	global_load_dwordx4 v[204:207], v[66:67], off offset:192
	global_load_dwordx4 v[208:211], v[70:71], off offset:192
	s_nop 0
	s_nop 0
	s_nop 0
	global_load_dwordx4 v[212:215], v[6:7], off offset:192
	s_nop 4
	s_nop 0
	s_nop 0
	s_nop 0
	s_nop 5
	s_nop 0
	s_nop 0
	s_nop 0
	s_nop 7
	s_nop 0
	s_waitcnt vmcnt(0)
	s_nop 0
	s_nop 0
	s_nop 0
	v_mfma_f32_16x16x32_bf16 v[30:33], v[76:79], v[84:87], 0
	s_nop 0
	s_nop 0
	v_mfma_f32_16x16x32_bf16 v[14:17], v[76:79], v[100:103], 0
	v_mfma_f32_16x16x32_bf16 v[38:41], v[88:91], v[84:87], 0
	v_mfma_f32_16x16x32_bf16 v[42:45], v[92:95], v[84:87], 0
	v_mfma_f32_16x16x32_bf16 v[18:21], v[96:99], v[84:87], 0
	v_mfma_f32_16x16x32_bf16 v[26:29], v[88:91], v[100:103], 0
	v_mfma_f32_16x16x32_bf16 v[34:37], v[92:95], v[100:103], 0
	v_mfma_f32_16x16x32_bf16 v[22:25], v[96:99], v[100:103], 0
	s_nop 0
	s_nop 0
	v_mfma_f32_16x16x32_bf16 v[30:33], v[80:83], v[116:119], v[30:33]
	v_mfma_f32_16x16x32_bf16 v[14:17], v[80:83], v[104:107], v[14:17]
	s_nop 0
	v_mfma_f32_16x16x32_bf16 v[42:45], v[108:111], v[116:119], v[42:45]
	v_mfma_f32_16x16x32_bf16 v[34:37], v[108:111], v[104:107], v[34:37]
	s_nop 0
	s_nop 0
	v_mfma_f32_16x16x32_bf16 v[38:41], v[120:123], v[116:119], v[38:41]
	v_mfma_f32_16x16x32_bf16 v[18:21], v[112:115], v[116:119], v[18:21]
	s_nop 0
	v_mfma_f32_16x16x32_bf16 v[26:29], v[120:123], v[104:107], v[26:29]
	s_nop 0
	v_mfma_f32_16x16x32_bf16 v[22:25], v[112:115], v[104:107], v[22:25]
	s_nop 0
	s_nop 0
	s_nop 0
	v_mfma_f32_16x16x32_bf16 v[30:33], v[148:151], v[152:155], v[30:33]
	v_mfma_f32_16x16x32_bf16 v[14:17], v[148:151], v[164:167], v[14:17]
	s_nop 0
	v_mfma_f32_16x16x32_bf16 v[42:45], v[124:127], v[152:155], v[42:45]
	v_mfma_f32_16x16x32_bf16 v[18:21], v[168:171], v[152:155], v[18:21]
	v_mfma_f32_16x16x32_bf16 v[34:37], v[124:127], v[164:167], v[34:37]
	s_nop 0
	v_mfma_f32_16x16x32_bf16 v[22:25], v[168:171], v[164:167], v[22:25]
	s_nop 0
	s_nop 0
	v_mfma_f32_16x16x32_bf16 v[38:41], v[172:175], v[152:155], v[38:41]
	s_nop 0
	v_mfma_f32_16x16x32_bf16 v[26:29], v[172:175], v[164:167], v[26:29]
	s_nop 0
	s_nop 0
	s_nop 0
	v_mfma_f32_16x16x32_bf16 v[42:45], v[176:179], v[184:187], v[42:45]
	v_mfma_f32_16x16x32_bf16 v[30:33], v[204:207], v[184:187], v[30:33]
	v_mfma_f32_16x16x32_bf16 v[38:41], v[208:211], v[184:187], v[38:41]
	v_mfma_f32_16x16x32_bf16 v[18:21], v[180:183], v[184:187], v[18:21]
	s_nop 0
	s_nop 4
	ds_write_b128 v12, v[30:33]
	ds_write_b128 v12, v[38:41] offset:64
	ds_write_b128 v12, v[42:45] offset:128
	ds_write_b128 v12, v[18:21] offset:192
	s_nop 0
	v_mfma_f32_16x16x32_bf16 v[14:17], v[204:207], v[212:215], v[14:17]
	v_mfma_f32_16x16x32_bf16 v[26:29], v[208:211], v[212:215], v[26:29]
	v_mfma_f32_16x16x32_bf16 v[18:21], v[176:179], v[212:215], v[34:37]
	s_nop 5
	ds_write_b128 v12, v[14:17] offset:4352
	ds_write_b128 v12, v[26:29] offset:4416
	ds_write_b128 v12, v[18:21] offset:4480
	v_mfma_f32_16x16x32_bf16 v[14:17], v[180:183], v[212:215], v[22:25]
	s_nop 7
	ds_write_b128 v12, v[14:17] offset:4544
	s_waitcnt lgkmcnt(0)
	s_barrier
	s_and_saveexec_b64 s[4:5], vcc
	s_cbranch_execz .LBB0_717
	v_add_u32_e32 v0, s12, v10
	s_mov_b64 s[12:13], 0
	v_mov_b32_e32 v6, v11
	v_mov_b32_e32 v7, v8
; #define LAS __attribute__((address_space(3)))
; __device__ __forceinline__ float bflo(unsigned w) { return __uint_as_float(w << 16); }
; __device__ __forceinline__ float bfhi(unsigned w) { return __uint_as_float(w & 0xffff0000u); }
; __device__ __forceinline__ unsigned pk2(float lo, float hi) { f32x2 v = {lo, hi}; bf16x2_t b = __builtin_convertvector(v, bf16x2_t); return __builtin_bit_cast(unsigned, b); }
; __device__ __forceinline__ float sigm(float x) { return __builtin_amdgcn_rcpf(1.f + __expf(-x)); }
;     template <int QPR> __device__ __forceinline__ void tailq(int row, int c, const f32x4 v, int) const { quad(row, c, v); }
;     template <int QPR> __device__ __forceinline__ void tailq(int row, int c, const f32x4 v, int) const { quad(row, c, v); }
;     __device__ __forceinline__ void quad(int row, int c, f32x4 v) const {
;         const u32x2 gw = *(const u32x2*)(Z + (size_t)row * NZ + ZC_MA + c);
;         v[0] *= sigm(bflo(gw.x)); v[1] *= sigm(bfhi(gw.x)); v[2] *= sigm(bflo(gw.y)); v[3] *= sigm(bfhi(gw.y));
;         u32x2 w; w.x = pk2(v[0], v[1]); w.y = pk2(v[2], v[3]); *(u32x2*)(T + (size_t)row * D + c) = w; }
; template <int MT, int NT, class Epi>
; __device__ __forceinline__ void tail_splitk(LAS unsigned char* lds, const bf16_t* A, const bf16_t* Bt, int K, int row_base, int n_rt, int col_base, int n_ct, int it0, const Epi& E) {
;     ...
;         for (int q = tid; q < MT * 16 * QPR; q += 512) { const int row = q / QPR, qc = q % QPR;
;             f32x4 v = {0.f, 0.f, 0.f, 0.f};
; #pragma unroll
;             for (int ww = 0; ww < 8; ++ww) v = v + *(const LAS f32x4*)(lds + ww * WB + (row * RS + qc * 4) * 4);
;             E.template tailq<QPR>(r0 + row, c0 + qc * 4, v, c0); }
.LBB0_720:
	v_ashrrev_i32_e32 v13, 31, v7
	v_lshrrev_b32_e32 v13, 28, v13
	v_add_u32_e32 v13, v7, v13
	v_ashrrev_i32_e32 v22, 4, v13
	v_and_b32_e32 v13, -16, v13
	v_add_u32_e32 v13, v6, v13
	ds_read_b128 v[216:219], v13
	ds_read_b128 v[220:223], v13 offset:8704
	ds_read_b128 v[224:227], v13 offset:17408
	ds_read_b128 v[228:231], v13 offset:26112
	ds_read_b128 v[232:235], v13 offset:34816
	ds_read_b128 v[236:239], v13 offset:43520
	ds_read_b128 v[240:243], v13 offset:52224
	ds_read_b128 v[14:17], v13 offset:60928
	v_add_u32_e32 v6, 0x2000, v6
	s_waitcnt lgkmcnt(7)
	v_pk_add_f32 v[18:19], v[218:219], 0 op_sel_hi:[1,0]
	v_pk_add_f32 v[20:21], v[216:217], 0 op_sel_hi:[1,0]
	s_waitcnt lgkmcnt(6)
	v_pk_add_f32 v[18:19], v[18:19], v[222:223]
	v_pk_add_f32 v[20:21], v[20:21], v[220:221]
	s_waitcnt lgkmcnt(5)
	v_pk_add_f32 v[18:19], v[18:19], v[226:227]
	v_pk_add_f32 v[20:21], v[20:21], v[224:225]
	s_waitcnt lgkmcnt(4)
	v_pk_add_f32 v[18:19], v[18:19], v[230:231]
	v_pk_add_f32 v[20:21], v[20:21], v[228:229]
	s_waitcnt lgkmcnt(3)
	v_pk_add_f32 v[18:19], v[18:19], v[234:235]
	v_pk_add_f32 v[20:21], v[20:21], v[232:233]
	s_waitcnt lgkmcnt(2)
	v_pk_add_f32 v[18:19], v[18:19], v[238:239]
	v_pk_add_f32 v[20:21], v[20:21], v[236:237]
	s_waitcnt lgkmcnt(1)
	v_pk_add_f32 v[18:19], v[18:19], v[242:243]
	v_pk_add_f32 v[20:21], v[20:21], v[240:241]
	v_lshlrev_b32_e32 v13, 6, v22
	s_waitcnt lgkmcnt(0)
	v_pk_add_f32 v[14:15], v[20:21], v[14:15]
	v_sub_u32_e32 v20, v0, v13
	v_pk_add_f32 v[16:17], v[18:19], v[16:17]
	v_add_u32_e32 v18, s15, v22
	v_mov_b64_e32 v[22:23], s[34:35]
	v_ashrrev_i32_e32 v21, 31, v20
	v_mad_i64_i32 v[22:23], s[0:1], v18, s67, v[22:23]
	v_lshlrev_b64 v[20:21], 1, v[20:21]
	v_lshl_add_u64 v[22:23], v[22:23], 0, v[20:21]
	v_add_co_u32_e64 v22, s[0:1], s7, v22
	v_ashrrev_i32_e32 v19, 31, v18
	s_nop 0
	v_addc_co_u32_e64 v23, s[0:1], 0, v23, s[0:1]
	v_cmp_lt_i32_e64 s[0:1], -1, v7
	v_add_u32_e32 v0, 0x800, v0
	s_or_b64 s[12:13], s[0:1], s[12:13]
	s_waitcnt vmcnt(0) lgkmcnt(0)
	v_lshlrev_b32_e32 v13, 16, v46
	v_mul_f32_e32 v13, 0xbfb8aa3b, v13
	v_exp_f32_e32 v13, v13
	s_nop 0
	v_add_f32_e32 v13, 1.0, v13
	v_rcp_f32_e32 v24, v13
	v_and_b32_e32 v13, 0xffff0000, v46
	v_mul_f32_e32 v13, 0xbfb8aa3b, v13
	v_exp_f32_e32 v13, v13
	s_nop 0
	v_add_f32_e32 v13, 1.0, v13
	v_rcp_f32_e32 v25, v13
	v_lshlrev_b32_e32 v13, 16, v47
	v_mul_f32_e32 v13, 0xbfb8aa3b, v13
	v_exp_f32_e32 v13, v13
	v_pk_mul_f32 v[14:15], v[14:15], v[24:25]
	v_add_f32_e32 v13, 1.0, v13
	v_rcp_f32_e32 v22, v13
	v_and_b32_e32 v13, 0xffff0000, v47
	v_mul_f32_e32 v13, 0xbfb8aa3b, v13
	v_exp_f32_e32 v13, v13
	v_cvt_pk_bf16_f32 v14, v14, v15
	v_add_f32_e32 v13, 1.0, v13
	v_rcp_f32_e32 v23, v13
	v_add_u32_e32 v13, 0x200, v7
	v_mov_b32_e32 v7, v13
	v_pk_mul_f32 v[16:17], v[16:17], v[22:23]
	s_nop 0
	v_cvt_pk_bf16_f32 v15, v16, v17
	v_lshlrev_b64 v[16:17], 11, v[18:19]
	v_lshl_add_u64 v[16:17], s[22:23], 0, v[16:17]
	v_lshl_add_u64 v[16:17], v[16:17], 0, v[20:21]
	flat_store_dwordx2 v[16:17], v[14:15]
	s_andn2_b64 exec, exec, s[12:13]
	s_cbranch_execnz .LBB0_720
	s_branch .LBB0_717

; #define LAS __attribute__((address_space(3)))
; __device__ __forceinline__ float bflo(unsigned w) { return __uint_as_float(w << 16); }
; __device__ __forceinline__ float bfhi(unsigned w) { return __uint_as_float(w & 0xffff0000u); }
; #define MFMA16(a, b, c) __builtin_amdgcn_mfma_f32_16x16x32_bf16((a), (b), (c), 0, 0, 0)
;     __device__ __forceinline__ void quad(int row, int c, const f32x4 a) const {
;         const u32x2 gw = *(const u32x2*)(Z + (size_t)row * NZ + ZC_MB + c);
;         const u32x2 tw = *(const u32x2*)(T + (size_t)row * D + c); const f32x4 t = {bflo(tw.x), bfhi(tw.x), bflo(tw.y), bfhi(tw.y)};
; template <int MT, int NT, class Epi>
; __device__ __forceinline__ void tail_splitk(LAS unsigned char* lds, const bf16_t* A, const bf16_t* Bt, int K, int row_base, int n_rt, int col_base, int n_ct, int it0, const Epi& E) {
;     ...
;     for (int it = (bid - it0 + G) % G; it < n_rt * n_ct; it += G) {
;         const int rt = it % n_rt, ct = it / n_rt, r0 = row_base + rt * 16 * MT, c0 = col_base + ct * 16 * NT;
;         f32x4 acc[MT][NT];
; #pragma unroll
;         for (int mt = 0; mt < MT; ++mt)
; #pragma unroll
;             for (int nt = 0; nt < NT; ++nt) acc[mt][nt] = (f32x4){0.f, 0.f, 0.f, 0.f};
;         const bf16_t* ap = A + (size_t)(r0 + fr) * K + fq * 8 + w * nks * 32; const bf16_t* bp = Bt + (size_t)(c0 + fr) * K + fq * 8 + w * nks * 32;
; #pragma unroll 4
;         for (int ks = 0; ks < nks; ++ks) {
;             bf16x8 af[MT], bfv[NT];
; #pragma unroll
;             for (int mt = 0; mt < MT; ++mt) af[mt] = *(const bf16x8*)(ap + (size_t)mt * 16 * K + ks * 32);
; #pragma unroll
;             for (int nt = 0; nt < NT; ++nt) bfv[nt] = *(const bf16x8*)(bp + (size_t)nt * 16 * K + ks * 32);
; #pragma unroll
;             for (int mt = 0; mt < MT; ++mt)
; #pragma unroll
;                 for (int nt = 0; nt < NT; ++nt) acc[mt][nt] = MFMA16(bfv[nt], af[mt], acc[mt][nt]);
;         }
;         LAS float* pw = (LAS float*)(lds + w * WB);
; #pragma unroll
;         for (int mt = 0; mt < MT; ++mt)
; #pragma unroll
;             for (int nt = 0; nt < NT; ++nt) *(LAS f32x4*)(pw + (16 * mt + fr) * RS + 16 * nt + 4 * fq) = acc[mt][nt];
;         __syncthreads();
.LBB0_802:
	s_ashr_i32 s0, s14, 31
	s_lshr_b32 s0, s0, 29
	s_add_i32 s0, s14, s0
	s_and_b32 s1, s0, 0x7fffff8
	s_lshl_b32 s12, s0, 3
	s_sub_i32 s1, s14, s1
	s_andn2_b32 s12, s12, 63
	s_lshl_b32 s15, s1, 5
	v_or_b32_e32 v6, s12, v9
	s_addk_i32 s15, 0x4000
	v_ashrrev_i32_e32 v7, 31, v6
	v_lshlrev_b64 v[6:7], 11, v[6:7]
	v_or_b32_e32 v0, s15, v9
	v_lshl_add_u64 v[66:67], v[4:5], 0, v[6:7]
	v_lshlrev_b64 v[6:7], 11, v[0:1]
	v_lshl_add_u64 v[68:69], v[2:3], 0, v[6:7]
	v_add_co_u32_e64 v6, s[0:1], s64, v68
	v_ashrrev_i32_e32 v48, 4, v8
	v_lshlrev_b32_e32 v49, 6, v48
	v_add_u32_e32 v50, s12, v10
	v_sub_u32_e32 v50, v50, v49
	v_add_u32_e32 v52, s15, v48
	v_ashrrev_i32_e32 v51, 31, v50
	v_ashrrev_i32_e32 v53, 31, v52
	v_mov_b64_e32 v[54:55], s[46:47]
	v_mad_i64_i32 v[54:55], s[86:87], v52, s67, v[54:55]
	v_lshlrev_b64 v[60:61], 1, v[50:51]
	v_lshl_add_u64 v[54:55], v[54:55], 0, v[60:61]
	v_add_co_u32_e64 v54, s[86:87], s2, v54
	s_nop 1
	v_addc_co_u32_e64 v55, s[86:87], 0, v55, s[86:87]
	global_load_dwordx2 v[46:47], v[54:55], off
	v_lshlrev_b64 v[58:59], 11, v[52:53]
	v_lshl_add_u64 v[58:59], s[42:43], 0, v[58:59]
	v_lshl_add_u64 v[58:59], v[50:51], 1, v[58:59]
	global_load_dwordx2 v[56:57], v[58:59], off
	global_load_dwordx4 v[76:79], v[66:67], off
	global_load_dwordx4 v[80:83], v[66:67], off offset:64
	v_addc_co_u32_e64 v7, s[0:1], 0, v69, s[0:1]
	v_add_co_u32_e64 v70, s[0:1], s64, v66
	global_load_dwordx4 v[84:87], v[68:69], off
	s_nop 0
	v_addc_co_u32_e64 v71, s[0:1], 0, v67, s[0:1]
	v_add_co_u32_e64 v72, s[0:1], s33, v66
	global_load_dwordx4 v[88:91], v[70:71], off
	s_nop 0
	v_addc_co_u32_e64 v73, s[0:1], 0, v67, s[0:1]
	v_add_co_u32_e64 v74, s[0:1], s6, v66
	global_load_dwordx4 v[92:95], v[72:73], off
	s_nop 0
	v_addc_co_u32_e64 v75, s[0:1], 0, v67, s[0:1]
	global_load_dwordx4 v[96:99], v[74:75], off
	global_load_dwordx4 v[100:103], v[6:7], off
	global_load_dwordx4 v[104:107], v[6:7], off offset:64
	s_nop 0
	s_nop 0
	global_load_dwordx4 v[108:111], v[72:73], off offset:64
	global_load_dwordx4 v[112:115], v[74:75], off offset:64
	s_nop 0
	s_nop 0
	s_nop 0
	global_load_dwordx4 v[116:119], v[68:69], off offset:64
	s_nop 0
	s_nop 0
	s_nop 0
	global_load_dwordx4 v[120:123], v[70:71], off offset:64
	s_nop 0
	s_nop 0
	global_load_dwordx4 v[124:127], v[72:73], off offset:128
	s_nop 0
	s_nop 0
	s_nop 0
	global_load_dwordx4 v[148:151], v[66:67], off offset:128
	s_nop 0
	global_load_dwordx4 v[152:155], v[68:69], off offset:128
	s_nop 0
	global_load_dwordx4 v[164:167], v[6:7], off offset:128
	global_load_dwordx4 v[168:171], v[74:75], off offset:128
	s_nop 0
	s_nop 0
	s_nop 0
	global_load_dwordx4 v[172:175], v[70:71], off offset:128
	s_nop 0
	s_nop 0
	s_nop 0
	global_load_dwordx4 v[176:179], v[72:73], off offset:192
	s_nop 0
	global_load_dwordx4 v[180:183], v[74:75], off offset:192
	s_nop 0
	s_nop 0
	global_load_dwordx4 v[184:187], v[68:69], off offset:192
	s_nop 0
	global_load_dwordx4 v[204:207], v[66:67], off offset:192
	global_load_dwordx4 v[208:211], v[70:71], off offset:192
	s_nop 0
	s_nop 0
	s_nop 0
	global_load_dwordx4 v[212:215], v[6:7], off offset:192
	s_nop 4
	s_nop 0
	s_nop 0
	s_nop 0
	s_nop 5
	s_nop 0
	s_nop 0
	s_nop 0
	s_nop 7
	s_nop 0
	s_waitcnt vmcnt(0)
	s_nop 0
	s_nop 0
	s_nop 0
	v_mfma_f32_16x16x32_bf16 v[30:33], v[76:79], v[84:87], 0
	s_nop 0
	s_nop 0
	v_mfma_f32_16x16x32_bf16 v[14:17], v[76:79], v[100:103], 0
	v_mfma_f32_16x16x32_bf16 v[38:41], v[88:91], v[84:87], 0
	v_mfma_f32_16x16x32_bf16 v[42:45], v[92:95], v[84:87], 0
	v_mfma_f32_16x16x32_bf16 v[18:21], v[96:99], v[84:87], 0
	v_mfma_f32_16x16x32_bf16 v[26:29], v[88:91], v[100:103], 0
	v_mfma_f32_16x16x32_bf16 v[34:37], v[92:95], v[100:103], 0
	v_mfma_f32_16x16x32_bf16 v[22:25], v[96:99], v[100:103], 0
	s_nop 0
	s_nop 0
	v_mfma_f32_16x16x32_bf16 v[30:33], v[80:83], v[116:119], v[30:33]
	v_mfma_f32_16x16x32_bf16 v[14:17], v[80:83], v[104:107], v[14:17]
	s_nop 0
	v_mfma_f32_16x16x32_bf16 v[42:45], v[108:111], v[116:119], v[42:45]
	v_mfma_f32_16x16x32_bf16 v[34:37], v[108:111], v[104:107], v[34:37]
	s_nop 0
	s_nop 0
	v_mfma_f32_16x16x32_bf16 v[38:41], v[120:123], v[116:119], v[38:41]
	v_mfma_f32_16x16x32_bf16 v[18:21], v[112:115], v[116:119], v[18:21]
	s_nop 0
	v_mfma_f32_16x16x32_bf16 v[26:29], v[120:123], v[104:107], v[26:29]
	s_nop 0
	v_mfma_f32_16x16x32_bf16 v[22:25], v[112:115], v[104:107], v[22:25]
	s_nop 0
	s_nop 0
	s_nop 0
	v_mfma_f32_16x16x32_bf16 v[30:33], v[148:151], v[152:155], v[30:33]
	v_mfma_f32_16x16x32_bf16 v[14:17], v[148:151], v[164:167], v[14:17]
	s_nop 0
	v_mfma_f32_16x16x32_bf16 v[42:45], v[124:127], v[152:155], v[42:45]
	v_mfma_f32_16x16x32_bf16 v[18:21], v[168:171], v[152:155], v[18:21]
	v_mfma_f32_16x16x32_bf16 v[34:37], v[124:127], v[164:167], v[34:37]
	s_nop 0
	v_mfma_f32_16x16x32_bf16 v[22:25], v[168:171], v[164:167], v[22:25]
	s_nop 0
	s_nop 0
	v_mfma_f32_16x16x32_bf16 v[38:41], v[172:175], v[152:155], v[38:41]
	s_nop 0
	v_mfma_f32_16x16x32_bf16 v[26:29], v[172:175], v[164:167], v[26:29]
	s_nop 0
	s_nop 0
	s_nop 0
	v_mfma_f32_16x16x32_bf16 v[42:45], v[176:179], v[184:187], v[42:45]
	v_mfma_f32_16x16x32_bf16 v[30:33], v[204:207], v[184:187], v[30:33]
	v_mfma_f32_16x16x32_bf16 v[38:41], v[208:211], v[184:187], v[38:41]
	v_mfma_f32_16x16x32_bf16 v[18:21], v[180:183], v[184:187], v[18:21]
	s_nop 0
	s_nop 4
	ds_write_b128 v12, v[30:33]
	ds_write_b128 v12, v[38:41] offset:64
	ds_write_b128 v12, v[42:45] offset:128
	ds_write_b128 v12, v[18:21] offset:192
	s_nop 0
	v_mfma_f32_16x16x32_bf16 v[14:17], v[204:207], v[212:215], v[14:17]
	v_mfma_f32_16x16x32_bf16 v[26:29], v[208:211], v[212:215], v[26:29]
	v_mfma_f32_16x16x32_bf16 v[18:21], v[176:179], v[212:215], v[34:37]
	s_nop 5
	ds_write_b128 v12, v[14:17] offset:4352
	ds_write_b128 v12, v[26:29] offset:4416
	ds_write_b128 v12, v[18:21] offset:4480
	v_mfma_f32_16x16x32_bf16 v[14:17], v[180:183], v[212:215], v[22:25]
	s_nop 7
	ds_write_b128 v12, v[14:17] offset:4544
	s_waitcnt lgkmcnt(0)
	s_barrier
	s_and_saveexec_b64 s[4:5], vcc
	s_cbranch_execz .LBB0_801
	v_add_u32_e32 v0, s12, v10
	s_mov_b64 s[12:13], 0
	v_mov_b32_e32 v13, v11
	v_mov_b32_e32 v14, v8
; #define LAS __attribute__((address_space(3)))
; __device__ __forceinline__ float bflo(unsigned w) { return __uint_as_float(w << 16); }
; __device__ __forceinline__ float bfhi(unsigned w) { return __uint_as_float(w & 0xffff0000u); }
; __device__ __forceinline__ unsigned pk2(float lo, float hi) { f32x2 v = {lo, hi}; bf16x2_t b = __builtin_convertvector(v, bf16x2_t); return __builtin_bit_cast(unsigned, b); }
; __device__ __forceinline__ float sigm(float x) { return __builtin_amdgcn_rcpf(1.f + __expf(-x)); }
;     template <int QPR> __device__ __forceinline__ void tailq(int row, int c, const f32x4 v, int) const { quad(row, c, v); }
;     template <int QPR> __device__ __forceinline__ void tailq(int row, int c, const f32x4 v, int) const { quad(row, c, v); }
;     __device__ __forceinline__ void quad(int row, int c, const f32x4 a) const {
;         const u32x2 gw = *(const u32x2*)(Z + (size_t)row * NZ + ZC_MB + c);
;         const u32x2 tw = *(const u32x2*)(T + (size_t)row * D + c); const f32x4 t = {bflo(tw.x), bfhi(tw.x), bflo(tw.y), bfhi(tw.y)};
;         const float v0 = t[0] + a[0] * sigm(bflo(gw.x)), v1 = t[1] + a[1] * sigm(bfhi(gw.x)), v2 = t[2] + a[2] * sigm(bflo(gw.y)), v3 = t[3] + a[3] * sigm(bfhi(gw.y));
;         u32x2 w; w.x = pk2(v0, v1); w.y = pk2(v2, v3);
;         *(u32x2*)(MG + (size_t)row * D + c) = w; }
; template <int MT, int NT, class Epi>
; __device__ __forceinline__ void tail_splitk(LAS unsigned char* lds, const bf16_t* A, const bf16_t* Bt, int K, int row_base, int n_rt, int col_base, int n_ct, int it0, const Epi& E) {
;     ...
;         for (int q = tid; q < MT * 16 * QPR; q += 512) { const int row = q / QPR, qc = q % QPR;
;             f32x4 v = {0.f, 0.f, 0.f, 0.f};
; #pragma unroll
;             for (int ww = 0; ww < 8; ++ww) v = v + *(const LAS f32x4*)(lds + ww * WB + (row * RS + qc * 4) * 4);
;             E.template tailq<QPR>(r0 + row, c0 + qc * 4, v, c0); }
.LBB0_804:
	v_ashrrev_i32_e32 v6, 31, v14
	v_lshrrev_b32_e32 v6, 28, v6
	v_add_u32_e32 v6, v14, v6
	v_ashrrev_i32_e32 v15, 4, v6
	v_and_b32_e32 v6, -16, v6
	v_add_u32_e32 v22, v13, v6
	ds_read_b128 v[216:219], v22
	ds_read_b128 v[220:223], v22 offset:8704
	ds_read_b128 v[224:227], v22 offset:17408
	ds_read_b128 v[228:231], v22 offset:26112
	ds_read_b128 v[232:235], v22 offset:34816
	ds_read_b128 v[236:239], v22 offset:43520
	ds_read_b128 v[240:243], v22 offset:52224
	ds_read_b128 v[16:19], v22 offset:60928
	v_add_u32_e32 v13, 0x2000, v13
	s_waitcnt lgkmcnt(7)
	v_pk_add_f32 v[6:7], v[218:219], 0 op_sel_hi:[1,0]
	v_pk_add_f32 v[20:21], v[216:217], 0 op_sel_hi:[1,0]
	s_waitcnt lgkmcnt(6)
	v_pk_add_f32 v[6:7], v[6:7], v[222:223]
	v_pk_add_f32 v[20:21], v[20:21], v[220:221]
	s_waitcnt lgkmcnt(5)
	v_pk_add_f32 v[6:7], v[6:7], v[226:227]
	v_pk_add_f32 v[20:21], v[20:21], v[224:225]
	s_waitcnt lgkmcnt(4)
	v_pk_add_f32 v[6:7], v[6:7], v[230:231]
	v_pk_add_f32 v[20:21], v[20:21], v[228:229]
	s_waitcnt lgkmcnt(3)
	v_pk_add_f32 v[6:7], v[6:7], v[234:235]
	v_pk_add_f32 v[20:21], v[20:21], v[232:233]
	s_waitcnt lgkmcnt(2)
	v_pk_add_f32 v[6:7], v[6:7], v[238:239]
	v_pk_add_f32 v[20:21], v[20:21], v[236:237]
	s_waitcnt lgkmcnt(1)
	v_pk_add_f32 v[6:7], v[6:7], v[242:243]
	v_pk_add_f32 v[20:21], v[20:21], v[240:241]
	v_mov_b64_e32 v[22:23], s[46:47]
	s_waitcnt lgkmcnt(0)
	v_pk_add_f32 v[6:7], v[6:7], v[18:19]
	v_add_u32_e32 v18, s15, v15
	v_lshlrev_b32_e32 v15, 6, v15
	v_pk_add_f32 v[16:17], v[20:21], v[16:17]
	v_sub_u32_e32 v20, v0, v15
	v_ashrrev_i32_e32 v21, 31, v20
	v_mad_i64_i32 v[22:23], s[0:1], v18, s67, v[22:23]
	v_lshlrev_b64 v[20:21], 1, v[20:21]
	v_lshl_add_u64 v[22:23], v[22:23], 0, v[20:21]
	v_add_co_u32_e64 v22, s[0:1], s2, v22
	v_ashrrev_i32_e32 v19, 31, v18
	s_nop 0
	v_addc_co_u32_e64 v23, s[0:1], 0, v23, s[0:1]
	v_lshlrev_b64 v[18:19], 11, v[18:19]
	v_lshl_add_u64 v[24:25], s[42:43], 0, v[18:19]
	v_lshl_add_u64 v[24:25], v[24:25], 0, v[20:21]
	v_cmp_lt_i32_e64 s[0:1], -1, v14
	v_add_u32_e32 v0, 0x800, v0
	s_or_b64 s[12:13], s[0:1], s[12:13]
	s_waitcnt vmcnt(0) lgkmcnt(0)
	v_lshlrev_b32_e32 v15, 16, v46
	v_mul_f32_e32 v15, 0xbfb8aa3b, v15
	v_exp_f32_e32 v15, v15
	v_lshlrev_b32_e32 v28, 16, v56
	v_and_b32_e32 v29, 0xffff0000, v56
	v_add_f32_e32 v15, 1.0, v15
	v_rcp_f32_e32 v26, v15
	v_and_b32_e32 v15, 0xffff0000, v46
	v_mul_f32_e32 v15, 0xbfb8aa3b, v15
	v_exp_f32_e32 v15, v15
	v_lshlrev_b32_e32 v24, 16, v57
	v_and_b32_e32 v25, 0xffff0000, v57
	v_add_f32_e32 v15, 1.0, v15
	v_rcp_f32_e32 v27, v15
	v_lshlrev_b32_e32 v15, 16, v47
	v_mul_f32_e32 v15, 0xbfb8aa3b, v15
	v_exp_f32_e32 v15, v15
	v_pk_fma_f32 v[16:17], v[16:17], v[26:27], v[28:29]
	v_add_f32_e32 v15, 1.0, v15
	v_rcp_f32_e32 v22, v15
	v_and_b32_e32 v15, 0xffff0000, v47
	v_mul_f32_e32 v15, 0xbfb8aa3b, v15
	v_exp_f32_e32 v15, v15
	v_cvt_pk_bf16_f32 v16, v16, v17
	v_add_f32_e32 v15, 1.0, v15
	v_rcp_f32_e32 v23, v15
	s_nop 0
	v_pk_fma_f32 v[6:7], v[6:7], v[22:23], v[24:25]
	s_nop 0
	v_cvt_pk_bf16_f32 v17, v6, v7
	v_lshl_add_u64 v[6:7], s[48:49], 0, v[18:19]
	v_lshl_add_u64 v[6:7], v[6:7], 0, v[20:21]
	flat_store_dwordx2 v[6:7], v[16:17]
	v_add_u32_e32 v6, 0x200, v14
	v_mov_b32_e32 v14, v6
	s_andn2_b64 exec, exec, s[12:13]
	s_cbranch_execnz .LBB0_804
	s_branch .LBB0_801

; #define LAS __attribute__((address_space(3)))
; #define MFMA16(a, b, c) __builtin_amdgcn_mfma_f32_16x16x32_bf16((a), (b), (c), 0, 0, 0)
;     __device__ __forceinline__ float quad(int row, int c, const f32x4 a) const {
;         bf16_t* xp = XB + (size_t)row * D + c;
;         const u32x2 xw = *(const u32x2*)xp;
; template <int MT, int NT, class Epi>
; __device__ __forceinline__ void tail_splitk(LAS unsigned char* lds, const bf16_t* A, const bf16_t* Bt, int K, int row_base, int n_rt, int col_base, int n_ct, int it0, const Epi& E) {
;     ...
;     for (int it = (bid - it0 + G) % G; it < n_rt * n_ct; it += G) {
;         const int rt = it % n_rt, ct = it / n_rt, r0 = row_base + rt * 16 * MT, c0 = col_base + ct * 16 * NT;
;         f32x4 acc[MT][NT];
; #pragma unroll
;         for (int mt = 0; mt < MT; ++mt)
; #pragma unroll
;             for (int nt = 0; nt < NT; ++nt) acc[mt][nt] = (f32x4){0.f, 0.f, 0.f, 0.f};
;         const bf16_t* ap = A + (size_t)(r0 + fr) * K + fq * 8 + w * nks * 32; const bf16_t* bp = Bt + (size_t)(c0 + fr) * K + fq * 8 + w * nks * 32;
; #pragma unroll 4
;         for (int ks = 0; ks < nks; ++ks) {
;             bf16x8 af[MT], bfv[NT];
; #pragma unroll
;             for (int mt = 0; mt < MT; ++mt) af[mt] = *(const bf16x8*)(ap + (size_t)mt * 16 * K + ks * 32);
; #pragma unroll
;             for (int nt = 0; nt < NT; ++nt) bfv[nt] = *(const bf16x8*)(bp + (size_t)nt * 16 * K + ks * 32);
; #pragma unroll
;             for (int mt = 0; mt < MT; ++mt)
; #pragma unroll
;                 for (int nt = 0; nt < NT; ++nt) acc[mt][nt] = MFMA16(bfv[nt], af[mt], acc[mt][nt]);
;         }
;         LAS float* pw = (LAS float*)(lds + w * WB);
; #pragma unroll
;         for (int mt = 0; mt < MT; ++mt)
; #pragma unroll
;             for (int nt = 0; nt < NT; ++nt) *(LAS f32x4*)(pw + (16 * mt + fr) * RS + 16 * nt + 4 * fq) = acc[mt][nt];
;         __syncthreads();
.LBB0_906:
	s_ashr_i32 s0, s30, 31
	s_lshr_b32 s0, s0, 29
	s_add_i32 s0, s30, s0
	s_ashr_i32 s38, s0, 3
	s_and_b32 s0, s0, 0x7fffff8
	s_sub_i32 s0, s30, s0
	s_lshl_b32 s40, s38, 6
	s_lshl_b32 s43, s0, 5
	v_or_b32_e32 v6, s40, v9
	s_addk_i32 s43, 0x4000
	v_ashrrev_i32_e32 v7, 31, v6
	v_lshlrev_b64 v[6:7], 11, v[6:7]
	v_or_b32_e32 v0, s43, v9
	v_lshl_add_u64 v[66:67], v[4:5], 0, v[6:7]
	v_lshlrev_b64 v[6:7], 11, v[0:1]
	v_lshl_add_u64 v[68:69], v[2:3], 0, v[6:7]
	v_add_co_u32_e64 v6, s[0:1], s64, v68
	v_ashrrev_i32_e32 v48, 4, v8
	v_lshlrev_b32_e32 v49, 6, v48
	v_add_u32_e32 v50, s40, v10
	v_sub_u32_e32 v50, v50, v49
	v_add_u32_e32 v52, s43, v48
	v_ashrrev_i32_e32 v51, 31, v50
	v_ashrrev_i32_e32 v53, 31, v52
	v_lshlrev_b64 v[54:55], 11, v[52:53]
	v_lshl_add_u64 v[54:55], s[14:15], 0, v[54:55]
	v_lshl_add_u64 v[54:55], v[50:51], 1, v[54:55]
	global_load_dwordx2 v[46:47], v[54:55], off
	global_load_dwordx4 v[76:79], v[66:67], off
	global_load_dwordx4 v[80:83], v[66:67], off offset:64
	v_addc_co_u32_e64 v7, s[0:1], 0, v69, s[0:1]
	v_add_co_u32_e64 v70, s[0:1], s64, v66
	global_load_dwordx4 v[84:87], v[68:69], off
	s_nop 0
	v_addc_co_u32_e64 v71, s[0:1], 0, v67, s[0:1]
	v_add_co_u32_e64 v72, s[0:1], s33, v66
	global_load_dwordx4 v[88:91], v[70:71], off
	s_nop 0
	v_addc_co_u32_e64 v73, s[0:1], 0, v67, s[0:1]
	v_add_co_u32_e64 v74, s[0:1], s6, v66
	global_load_dwordx4 v[92:95], v[72:73], off
	s_nop 0
	v_addc_co_u32_e64 v75, s[0:1], 0, v67, s[0:1]
	global_load_dwordx4 v[96:99], v[74:75], off
	global_load_dwordx4 v[100:103], v[6:7], off
	global_load_dwordx4 v[104:107], v[6:7], off offset:64
	s_nop 0
	s_nop 0
	global_load_dwordx4 v[108:111], v[72:73], off offset:64
	global_load_dwordx4 v[112:115], v[74:75], off offset:64
	s_nop 0
	s_nop 0
	s_nop 0
	global_load_dwordx4 v[116:119], v[68:69], off offset:64
	s_nop 0
	s_nop 0
	s_nop 0
	global_load_dwordx4 v[120:123], v[70:71], off offset:64
	s_nop 0
	s_nop 0
	global_load_dwordx4 v[124:127], v[72:73], off offset:128
	s_nop 0
	s_nop 0
	s_nop 0
	global_load_dwordx4 v[148:151], v[66:67], off offset:128
	s_nop 0
	global_load_dwordx4 v[152:155], v[68:69], off offset:128
	s_nop 0
	global_load_dwordx4 v[164:167], v[6:7], off offset:128
	global_load_dwordx4 v[168:171], v[74:75], off offset:128
	s_nop 0
	s_nop 0
	s_nop 0
	global_load_dwordx4 v[172:175], v[70:71], off offset:128
	s_nop 0
	s_nop 0
	s_nop 0
	global_load_dwordx4 v[176:179], v[72:73], off offset:192
	s_nop 0
	global_load_dwordx4 v[180:183], v[74:75], off offset:192
	s_nop 0
	s_nop 0
	global_load_dwordx4 v[184:187], v[68:69], off offset:192
	s_nop 0
	global_load_dwordx4 v[204:207], v[66:67], off offset:192
	global_load_dwordx4 v[208:211], v[70:71], off offset:192
	s_nop 0
	s_nop 0
	s_nop 0
	global_load_dwordx4 v[212:215], v[6:7], off offset:192
	s_nop 4
	s_nop 0
	s_nop 0
	s_nop 0
	s_nop 5
	s_nop 0
	s_nop 0
	s_nop 0
	s_nop 7
	s_nop 0
	s_waitcnt vmcnt(0)
	s_nop 0
	s_nop 0
	s_nop 0
	v_mfma_f32_16x16x32_bf16 v[30:33], v[76:79], v[84:87], 0
	s_nop 0
	s_nop 0
	v_mfma_f32_16x16x32_bf16 v[14:17], v[76:79], v[100:103], 0
	v_mfma_f32_16x16x32_bf16 v[38:41], v[88:91], v[84:87], 0
	v_mfma_f32_16x16x32_bf16 v[42:45], v[92:95], v[84:87], 0
	v_mfma_f32_16x16x32_bf16 v[18:21], v[96:99], v[84:87], 0
	v_mfma_f32_16x16x32_bf16 v[26:29], v[88:91], v[100:103], 0
	v_mfma_f32_16x16x32_bf16 v[34:37], v[92:95], v[100:103], 0
	v_mfma_f32_16x16x32_bf16 v[22:25], v[96:99], v[100:103], 0
	s_nop 0
	s_nop 0
	v_mfma_f32_16x16x32_bf16 v[30:33], v[80:83], v[116:119], v[30:33]
	v_mfma_f32_16x16x32_bf16 v[14:17], v[80:83], v[104:107], v[14:17]
	s_nop 0
	v_mfma_f32_16x16x32_bf16 v[42:45], v[108:111], v[116:119], v[42:45]
	v_mfma_f32_16x16x32_bf16 v[34:37], v[108:111], v[104:107], v[34:37]
	s_nop 0
	s_nop 0
	v_mfma_f32_16x16x32_bf16 v[38:41], v[120:123], v[116:119], v[38:41]
	v_mfma_f32_16x16x32_bf16 v[18:21], v[112:115], v[116:119], v[18:21]
	s_nop 0
	v_mfma_f32_16x16x32_bf16 v[26:29], v[120:123], v[104:107], v[26:29]
	s_nop 0
	v_mfma_f32_16x16x32_bf16 v[22:25], v[112:115], v[104:107], v[22:25]
	s_nop 0
	s_nop 0
	s_nop 0
	v_mfma_f32_16x16x32_bf16 v[30:33], v[148:151], v[152:155], v[30:33]
	v_mfma_f32_16x16x32_bf16 v[14:17], v[148:151], v[164:167], v[14:17]
	s_nop 0
	v_mfma_f32_16x16x32_bf16 v[42:45], v[124:127], v[152:155], v[42:45]
	v_mfma_f32_16x16x32_bf16 v[18:21], v[168:171], v[152:155], v[18:21]
	v_mfma_f32_16x16x32_bf16 v[34:37], v[124:127], v[164:167], v[34:37]
	s_nop 0
	v_mfma_f32_16x16x32_bf16 v[22:25], v[168:171], v[164:167], v[22:25]
	s_nop 0
	s_nop 0
	v_mfma_f32_16x16x32_bf16 v[38:41], v[172:175], v[152:155], v[38:41]
	s_nop 0
	v_mfma_f32_16x16x32_bf16 v[26:29], v[172:175], v[164:167], v[26:29]
	s_nop 0
	s_nop 0
	s_nop 0
	v_mfma_f32_16x16x32_bf16 v[42:45], v[176:179], v[184:187], v[42:45]
	v_mfma_f32_16x16x32_bf16 v[30:33], v[204:207], v[184:187], v[30:33]
	v_mfma_f32_16x16x32_bf16 v[38:41], v[208:211], v[184:187], v[38:41]
	v_mfma_f32_16x16x32_bf16 v[18:21], v[180:183], v[184:187], v[18:21]
	s_nop 0
	s_nop 4
	ds_write_b128 v12, v[30:33]
	ds_write_b128 v12, v[38:41] offset:64
	ds_write_b128 v12, v[42:45] offset:128
	ds_write_b128 v12, v[18:21] offset:192
	s_nop 0
	v_mfma_f32_16x16x32_bf16 v[14:17], v[204:207], v[212:215], v[14:17]
	v_mfma_f32_16x16x32_bf16 v[26:29], v[208:211], v[212:215], v[26:29]
	v_mfma_f32_16x16x32_bf16 v[18:21], v[176:179], v[212:215], v[34:37]
	s_nop 5
	ds_write_b128 v12, v[14:17] offset:4352
	ds_write_b128 v12, v[26:29] offset:4416
	ds_write_b128 v12, v[18:21] offset:4480
	v_mfma_f32_16x16x32_bf16 v[14:17], v[180:183], v[212:215], v[22:25]
	s_nop 7
	ds_write_b128 v12, v[14:17] offset:4544
	s_waitcnt lgkmcnt(0)
	s_barrier
	s_and_saveexec_b64 s[4:5], vcc
	s_cbranch_execz .LBB0_905
	v_and_b32_e32 v0, 64, v203
	v_add_u32_e32 v6, 64, v0
	v_xor_b32_e32 v0, 1, v203
	v_cmp_lt_i32_e64 s[0:1], v0, v6
	v_xor_b32_e32 v7, 2, v203
	s_ashr_i32 s39, s38, 31
	v_cndmask_b32_e64 v0, v203, v0, s[0:1]
	v_cmp_lt_i32_e64 s[0:1], v7, v6
	v_lshlrev_b32_e32 v0, 2, v0
	v_add_u32_e32 v16, s40, v10
	v_cndmask_b32_e64 v7, v203, v7, s[0:1]
	v_lshlrev_b32_e32 v13, 2, v7
	v_xor_b32_e32 v7, 4, v203
	v_cmp_lt_i32_e64 s[0:1], v7, v6
	s_mov_b64 s[40:41], 0
	v_mov_b32_e32 v17, v11
	v_cndmask_b32_e64 v7, v203, v7, s[0:1]
	v_lshlrev_b32_e32 v14, 2, v7
	v_xor_b32_e32 v7, 8, v203
	v_cmp_lt_i32_e64 s[0:1], v7, v6
	v_mov_b32_e32 v18, v8
	s_nop 0
	v_cndmask_b32_e64 v6, v203, v7, s[0:1]
	s_lshl_b64 s[0:1], s[38:39], 2
	s_add_u32 s38, s22, s0
	v_lshlrev_b32_e32 v15, 2, v6
	s_addc_u32 s39, s23, s1
	s_branch .LBB0_909

; #define LAS __attribute__((address_space(3)))
; __device__ __forceinline__ float bflo(unsigned w) { return __uint_as_float(w << 16); }
; __device__ __forceinline__ float bfhi(unsigned w) { return __uint_as_float(w & 0xffff0000u); }
; __device__ __forceinline__ unsigned pk2(float lo, float hi) { f32x2 v = {lo, hi}; bf16x2_t b = __builtin_convertvector(v, bf16x2_t); return __builtin_bit_cast(unsigned, b); }
;     template <int QPR> __device__ __forceinline__ void tailq(int row, int c, const f32x4 v, int) const { quad(row, c, v); }
;     template <int QPR> __device__ __forceinline__ void tailq(int row, int c, const f32x4 v, int) const { quad(row, c, v); }
;     __device__ __forceinline__ float quad(int row, int c, const f32x4 a) const {
;         bf16_t* xp = XB + (size_t)row * D + c;
;         const u32x2 xw = *(const u32x2*)xp;
;         const f32x4 x = (f32x4){bflo(xw.x), bfhi(xw.x), bflo(xw.y), bfhi(xw.y)} + a;
;         u32x2 w; w.x = pk2(x[0], x[1]); w.y = pk2(x[2], x[3]);
;         *(u32x2*)xp = w;
;         return (x[0] * x[0] + x[1] * x[1]) + (x[2] * x[2] + x[3] * x[3]); }
;     template <int QPR> __device__ __forceinline__ void tailq(int row, int c, const f32x4 v, int c0) const {
;         float sq = quad(row, c, v);
; #pragma unroll
;         for (int o = 1; o < QPR; o <<= 1) sq += __shfl_xor(sq, o);
;         if ((threadIdx.x & (QPR - 1)) == 0) ss[(size_t)row * 16 + (c0 >> 6)] = sq; }
; template <int MT, int NT, class Epi>
; __device__ __forceinline__ void tail_splitk(LAS unsigned char* lds, const bf16_t* A, const bf16_t* Bt, int K, int row_base, int n_rt, int col_base, int n_ct, int it0, const Epi& E) {
;     ...
;         for (int q = tid; q < MT * 16 * QPR; q += 512) { const int row = q / QPR, qc = q % QPR;
;             f32x4 v = {0.f, 0.f, 0.f, 0.f};
; #pragma unroll
;             for (int ww = 0; ww < 8; ++ww) v = v + *(const LAS f32x4*)(lds + ww * WB + (row * RS + qc * 4) * 4);
;             E.template tailq<QPR>(r0 + row, c0 + qc * 4, v, c0); }
.LBB0_909:
	v_ashrrev_i32_e32 v6, 31, v18
	v_lshrrev_b32_e32 v6, 28, v6
	v_add_u32_e32 v6, v18, v6
	v_ashrrev_i32_e32 v19, 4, v6
	v_and_b32_e32 v6, -16, v6
	v_add_u32_e32 v26, v17, v6
	s_waitcnt lgkmcnt(0)
	ds_read_b128 v[216:219], v26
	ds_read_b128 v[220:223], v26 offset:8704
	ds_read_b128 v[224:227], v26 offset:17408
	ds_read_b128 v[228:231], v26 offset:26112
	ds_read_b128 v[232:235], v26 offset:34816
	ds_read_b128 v[236:239], v26 offset:43520
	ds_read_b128 v[240:243], v26 offset:52224
	ds_read_b128 v[20:23], v26 offset:60928
	s_waitcnt lgkmcnt(7)
	v_pk_add_f32 v[6:7], v[218:219], 0 op_sel_hi:[1,0]
	v_pk_add_f32 v[24:25], v[216:217], 0 op_sel_hi:[1,0]
	s_waitcnt lgkmcnt(6)
	v_pk_add_f32 v[6:7], v[6:7], v[222:223]
	v_pk_add_f32 v[24:25], v[24:25], v[220:221]
	s_waitcnt lgkmcnt(5)
	v_pk_add_f32 v[6:7], v[6:7], v[226:227]
	v_pk_add_f32 v[24:25], v[24:25], v[224:225]
	s_waitcnt lgkmcnt(4)
	v_pk_add_f32 v[6:7], v[6:7], v[230:231]
	v_pk_add_f32 v[24:25], v[24:25], v[228:229]
	s_waitcnt lgkmcnt(3)
	v_pk_add_f32 v[6:7], v[6:7], v[234:235]
	v_pk_add_f32 v[24:25], v[24:25], v[232:233]
	s_waitcnt lgkmcnt(2)
	v_pk_add_f32 v[6:7], v[6:7], v[238:239]
	v_pk_add_f32 v[24:25], v[24:25], v[236:237]
	s_waitcnt lgkmcnt(1)
	v_pk_add_f32 v[6:7], v[6:7], v[242:243]
	v_pk_add_f32 v[24:25], v[24:25], v[240:241]
	s_waitcnt lgkmcnt(0)
	v_pk_add_f32 v[22:23], v[6:7], v[22:23]
	v_add_u32_e32 v6, s43, v19
	v_lshlrev_b32_e32 v7, 6, v19
	v_pk_add_f32 v[20:21], v[24:25], v[20:21]
	v_sub_u32_e32 v24, v16, v7
	v_ashrrev_i32_e32 v7, 31, v6
	v_lshlrev_b64 v[26:27], 11, v[6:7]
	v_lshl_add_u64 v[26:27], s[14:15], 0, v[26:27]
	v_ashrrev_i32_e32 v25, 31, v24
	v_lshl_add_u64 v[24:25], v[24:25], 1, v[26:27]
	s_waitcnt vmcnt(0) lgkmcnt(0)
	v_lshlrev_b32_e32 v28, 16, v46
	v_and_b32_e32 v29, 0xffff0000, v46
	v_lshlrev_b32_e32 v26, 16, v47
	v_and_b32_e32 v27, 0xffff0000, v47
	v_pk_add_f32 v[20:21], v[20:21], v[28:29]
	v_pk_add_f32 v[22:23], v[22:23], v[26:27]
	v_mul_f32_e32 v19, v21, v21
	v_cvt_pk_bf16_f32 v26, v20, v21
	v_fmac_f32_e32 v19, v20, v20
	v_mul_f32_e32 v20, v23, v23
	v_fmac_f32_e32 v20, v22, v22
	v_add_f32_e32 v19, v19, v20
	ds_bpermute_b32 v20, v0, v19
	v_cvt_pk_bf16_f32 v27, v22, v23
	flat_store_dwordx2 v[24:25], v[26:27]
	s_waitcnt lgkmcnt(0)
	v_add_f32_e32 v19, v19, v20
	ds_bpermute_b32 v20, v13, v19
	s_waitcnt lgkmcnt(0)
	v_add_f32_e32 v19, v19, v20
	ds_bpermute_b32 v20, v14, v19
	s_waitcnt lgkmcnt(0)
	v_add_f32_e32 v19, v19, v20
	ds_bpermute_b32 v20, v15, v19
	s_and_saveexec_b64 s[0:1], s[36:37]
	s_cbranch_execz .LBB0_908
	v_lshlrev_b64 v[6:7], 6, v[6:7]
	v_lshl_add_u64 v[6:7], s[38:39], 0, v[6:7]
	s_waitcnt lgkmcnt(0)
	v_add_f32_e32 v19, v19, v20
	flat_store_dword v[6:7], v19
	s_branch .LBB0_908

;     __device__ __forceinline__ float quad(int row, int c, const f32x4 a) const {
;         bf16_t* xp = XB + (size_t)row * D + c;
;         const u32x2 xw = *(const u32x2*)xp;
; template <int MT, int NT, class Epi>
; __device__ __forceinline__ void tail_splitk(LAS unsigned char* lds, const bf16_t* A, const bf16_t* Bt, int K, int row_base, int n_rt, int col_base, int n_ct, int it0, const Epi& E) {
;     ...
;     for (int it = (bid - it0 + G) % G; it < n_rt * n_ct; it += G) {
;         const int rt = it % n_rt, ct = it / n_rt, r0 = row_base + rt * 16 * MT, c0 = col_base + ct * 16 * NT;
;         f32x4 acc[MT][NT];
; #pragma unroll
;         for (int mt = 0; mt < MT; ++mt)
; #pragma unroll
;             for (int nt = 0; nt < NT; ++nt) acc[mt][nt] = (f32x4){0.f, 0.f, 0.f, 0.f};
;         const bf16_t* ap = A + (size_t)(r0 + fr) * K + fq * 8 + w * nks * 32; const bf16_t* bp = Bt + (size_t)(c0 + fr) * K + fq * 8 + w * nks * 32;
.LBB0_1168:
	s_ashr_i32 s0, s30, 31
	s_lshr_b32 s0, s0, 29
	s_add_i32 s0, s30, s0
	s_ashr_i32 s4, s0, 3
	v_lshl_add_u32 v2, s30, 5, v53
	s_lshl_b32 s0, s4, 8
	s_lshl_b32 s40, s4, 6
	v_subrev_u32_e32 v2, s0, v2
	s_movk_i32 s5, 0x1800
	v_mad_u64_u32 v[38:39], s[0:1], v2, s5, v[34:35]
	v_or_b32_e32 v2, s40, v52
	v_mad_i64_i32 v[40:41], s[0:1], v2, s5, v[36:37]
	v_mov_b32_e32 v2, 0
	s_mov_b64 s[38:39], 0
	v_mov_b32_e32 v3, v2
	v_mov_b32_e32 v4, v2
	v_mov_b32_e32 v5, v2
	v_mov_b32_e32 v6, v2
	v_mov_b32_e32 v7, v2
	v_mov_b32_e32 v8, v2
	v_mov_b32_e32 v9, v2
	v_mov_b32_e32 v10, v2
	v_mov_b32_e32 v11, v2
	v_mov_b32_e32 v12, v2
	v_mov_b32_e32 v13, v2
	v_mov_b32_e32 v14, v2
	v_mov_b32_e32 v15, v2
	v_mov_b32_e32 v16, v2
	v_mov_b32_e32 v17, v2
	v_mov_b32_e32 v18, v2
	v_mov_b32_e32 v19, v2
	v_mov_b32_e32 v20, v2
	v_mov_b32_e32 v21, v2
	v_mov_b32_e32 v22, v2
	v_mov_b32_e32 v23, v2
	v_mov_b32_e32 v24, v2
	v_mov_b32_e32 v25, v2
	v_mov_b32_e32 v26, v2
	v_mov_b32_e32 v27, v2
	v_mov_b32_e32 v28, v2
	v_mov_b32_e32 v29, v2
	v_mov_b32_e32 v30, v2
	v_mov_b32_e32 v31, v2
	v_mov_b32_e32 v32, v2
	v_mov_b32_e32 v33, v2
	s_lshl_b32 s88, s4, 3
	s_sub_i32 s88, s30, s88
	s_lshl_b32 s88, s88, 5
	s_addk_i32 s88, 0x4000
	v_ashrrev_i32_e32 v66, 4, v0
	v_lshlrev_b32_e32 v67, 6, v66
	v_add_u32_e32 v68, s40, v54
	v_sub_u32_e32 v68, v68, v67
	v_add_u32_e32 v70, s88, v66
	v_ashrrev_i32_e32 v69, 31, v68
	v_ashrrev_i32_e32 v71, 31, v70
	v_lshlrev_b64 v[72:73], 11, v[70:71]
	v_lshl_add_u64 v[72:73], s[12:13], 0, v[72:73]
	v_lshl_add_u64 v[72:73], v[68:69], 1, v[72:73]
	global_load_dwordx2 v[64:65], v[72:73], off

; #define LAS __attribute__((address_space(3)))
; __device__ __forceinline__ float bflo(unsigned w) { return __uint_as_float(w << 16); }
; __device__ __forceinline__ float bfhi(unsigned w) { return __uint_as_float(w & 0xffff0000u); }
; __device__ __forceinline__ unsigned pk2(float lo, float hi) { f32x2 v = {lo, hi}; bf16x2_t b = __builtin_convertvector(v, bf16x2_t); return __builtin_bit_cast(unsigned, b); }
;     template <int QPR> __device__ __forceinline__ void tailq(int row, int c, const f32x4 v, int) const { quad(row, c, v); }
;     template <int QPR> __device__ __forceinline__ void tailq(int row, int c, const f32x4 v, int) const { quad(row, c, v); }
;     __device__ __forceinline__ float quad(int row, int c, const f32x4 a) const {
;         bf16_t* xp = XB + (size_t)row * D + c;
;         const u32x2 xw = *(const u32x2*)xp;
;         const f32x4 x = (f32x4){bflo(xw.x), bfhi(xw.x), bflo(xw.y), bfhi(xw.y)} + a;
;         u32x2 w; w.x = pk2(x[0], x[1]); w.y = pk2(x[2], x[3]);
;         *(u32x2*)xp = w;
;         return (x[0] * x[0] + x[1] * x[1]) + (x[2] * x[2] + x[3] * x[3]); }
;     template <int QPR> __device__ __forceinline__ void tailq(int row, int c, const f32x4 v, int c0) const {
;         float sq = quad(row, c, v);
; #pragma unroll
;         for (int o = 1; o < QPR; o <<= 1) sq += __shfl_xor(sq, o);
;         if ((threadIdx.x & (QPR - 1)) == 0) ss[(size_t)row * 16 + (c0 >> 6)] = sq; }
; template <int MT, int NT, class Epi>
; __device__ __forceinline__ void tail_splitk(LAS unsigned char* lds, const bf16_t* A, const bf16_t* Bt, int K, int row_base, int n_rt, int col_base, int n_ct, int it0, const Epi& E) {
;     ...
;         for (int q = tid; q < MT * 16 * QPR; q += 512) { const int row = q / QPR, qc = q % QPR;
;             f32x4 v = {0.f, 0.f, 0.f, 0.f};
; #pragma unroll
;             for (int ww = 0; ww < 8; ++ww) v = v + *(const LAS f32x4*)(lds + ww * WB + (row * RS + qc * 4) * 4);
;             E.template tailq<QPR>(r0 + row, c0 + qc * 4, v, c0); }
.LBB0_1173:
	v_ashrrev_i32_e32 v2, 31, v10
	v_lshrrev_b32_e32 v2, 28, v2
	v_add_u32_e32 v2, v10, v2
	v_ashrrev_i32_e32 v11, 4, v2
	v_and_b32_e32 v2, -16, v2
	v_add_u32_e32 v18, v9, v2
	s_waitcnt lgkmcnt(0)
	ds_read_b128 v[224:227], v18
	ds_read_b128 v[228:231], v18 offset:8704
	ds_read_b128 v[232:235], v18 offset:17408
	ds_read_b128 v[236:239], v18 offset:26112
	ds_read_b128 v[240:243], v18 offset:34816
	ds_read_b128 v[244:247], v18 offset:43520
	ds_read_b128 v[58:61], v18 offset:52224
	ds_read_b128 v[12:15], v18 offset:60928
	s_waitcnt lgkmcnt(7)
	v_pk_add_f32 v[2:3], v[226:227], 0 op_sel_hi:[1,0]
	v_pk_add_f32 v[16:17], v[224:225], 0 op_sel_hi:[1,0]
	s_waitcnt lgkmcnt(6)
	v_pk_add_f32 v[2:3], v[2:3], v[230:231]
	v_pk_add_f32 v[16:17], v[16:17], v[228:229]
	s_waitcnt lgkmcnt(5)
	v_pk_add_f32 v[2:3], v[2:3], v[234:235]
	v_pk_add_f32 v[16:17], v[16:17], v[232:233]
	s_waitcnt lgkmcnt(4)
	v_pk_add_f32 v[2:3], v[2:3], v[238:239]
	v_pk_add_f32 v[16:17], v[16:17], v[236:237]
	s_waitcnt lgkmcnt(3)
	v_pk_add_f32 v[2:3], v[2:3], v[242:243]
	v_pk_add_f32 v[16:17], v[16:17], v[240:241]
	s_waitcnt lgkmcnt(2)
	v_pk_add_f32 v[2:3], v[2:3], v[246:247]
	v_pk_add_f32 v[16:17], v[16:17], v[244:245]
	s_waitcnt lgkmcnt(1)
	v_pk_add_f32 v[2:3], v[2:3], v[60:61]
	v_pk_add_f32 v[16:17], v[16:17], v[58:59]
	s_waitcnt lgkmcnt(0)
	v_pk_add_f32 v[14:15], v[2:3], v[14:15]
	v_add_u32_e32 v2, s52, v11
	v_lshlrev_b32_e32 v3, 6, v11
	v_pk_add_f32 v[12:13], v[16:17], v[12:13]
	v_sub_u32_e32 v16, v8, v3
	v_ashrrev_i32_e32 v3, 31, v2
	v_lshlrev_b64 v[18:19], 11, v[2:3]
	v_lshl_add_u64 v[18:19], s[12:13], 0, v[18:19]
	v_ashrrev_i32_e32 v17, 31, v16
	v_lshl_add_u64 v[16:17], v[16:17], 1, v[18:19]
	s_waitcnt vmcnt(0) lgkmcnt(0)
	v_lshlrev_b32_e32 v20, 16, v64
	v_and_b32_e32 v21, 0xffff0000, v64
	v_lshlrev_b32_e32 v18, 16, v65
	v_and_b32_e32 v19, 0xffff0000, v65
	v_pk_add_f32 v[12:13], v[12:13], v[20:21]
	v_pk_add_f32 v[14:15], v[14:15], v[18:19]
	v_mul_f32_e32 v11, v13, v13
	v_cvt_pk_bf16_f32 v18, v12, v13
	v_fmac_f32_e32 v11, v12, v12
	v_mul_f32_e32 v12, v15, v15
	v_fmac_f32_e32 v12, v14, v14
	v_add_f32_e32 v11, v11, v12
	ds_bpermute_b32 v12, v4, v11
	v_cvt_pk_bf16_f32 v19, v14, v15
	flat_store_dwordx2 v[16:17], v[18:19]
	s_waitcnt lgkmcnt(0)
	v_add_f32_e32 v11, v11, v12
	ds_bpermute_b32 v12, v5, v11
	s_waitcnt lgkmcnt(0)
	v_add_f32_e32 v11, v11, v12
	ds_bpermute_b32 v12, v6, v11
	s_waitcnt lgkmcnt(0)
	v_add_f32_e32 v11, v11, v12
	ds_bpermute_b32 v12, v7, v11
	s_and_saveexec_b64 s[0:1], s[36:37]
	s_cbranch_execz .LBB0_1172
	v_lshlrev_b64 v[2:3], 6, v[2:3]
	v_lshl_add_u64 v[2:3], s[4:5], 0, v[2:3]
	s_waitcnt lgkmcnt(0)
	v_add_f32_e32 v11, v11, v12
	flat_store_dword v[2:3], v11
	s_branch .LBB0_1172
